# stack8 plus GEMM phase heads: all fourteen initial stage loads issued before the first wait and barrier
# baseline (speedup 1.0000x reference)
; #define PG8_STAGE(bufoff, gbase, voff) do { _Pragma("unroll") for (int _i = 0; _i < 2; ++_i) \
;         __builtin_amdgcn_global_load_lds((const unsigned*)((const char*)(gbase) + (voff)[_i]), (LAS unsigned*)(lds + (bufoff) + ldsw + _i * 8192), 16, 0, 0); } while (0)
; #define PG8_WAIT_V(n) asm volatile("s_waitcnt vmcnt(" #n ")" ::: "memory")
; #define PG8_BAR __builtin_amdgcn_s_barrier()
; template <class Epi, bool SP2 = true, bool ALIGN_EPI = true>
; __device__ __forceinline__ void gemm_phase(LAS unsigned char* lds, const Gemm g, const StaticOrder& S, const Epi& E, const int tid) {
;     ...
;     for (int i = 0; i < 2; ++i) { int R, C; stage_rc(tid * 16 + i * 8192, R, C); const int Rb = Epi::PERM ? ((R & ~31) + perm32(R & 31)) : R;
;         voffA[i] = (unsigned)(R * K + C) * 2u; voffB[i] = (unsigned)(Rb * K + C) * 2u; }
;     const size_t kstep = (size_t)(BK * 2);
;     const size_t hstep = (size_t)HALF * K * 2;
;     const size_t tstep = 2 * hstep;
;     const unsigned ldsw = (unsigned)wid * 1024u;
;     const int aoff = lds_byte(wr * 64 + fr, fq * 8), boff = lds_byte(wc * 32 + fr, fq * 8);
;     ...
;     const char* cA = (const char*)g.A + (size_t)cur.pm * tstep; const char* cB = (const char*)g.Bt + (size_t)cur.pn * tstep;
;     if constexpr (SP2) {
;         PG8_STAGE(PG8_SB(0, 0), cB, voffB); PG8_STAGE(PG8_SB(0, 1), cB + hstep, voffB); PG8_STAGE(PG8_SA(0, 0), cA, voffA); PG8_STAGE(PG8_SA(0, 1), cA + hstep, voffA);
;         if (wr == 1) PG8_BAR;
;         PG8_WAIT_V(2); PG8_BAR;
;         PG8_STAGE(PG8_SB(1, 0), cB + kstep, voffB); PG8_STAGE(PG8_SA(1, 0), cA + kstep, voffA); PG8_STAGE(PG8_SB(1, 1), cB + hstep + kstep, voffB);
;         PG8_WAIT_V(6); PG8_BAR;
.LBB0_125:
	v_bfe_u32 v233, v231, 4, 2
	v_readlane_b32 s28, v250, 38
	v_and_b32_e32 v232, 15, v231
	v_lshlrev_b32_e32 v14, 4, v233
	v_lshlrev_b32_e32 v15, 2, v231
	v_readlane_b32 s29, v250, 39
	v_lshl_or_b32 v14, v232, 6, v14
	s_lshl_b32 s12, s20, 13
	v_and_b32_e32 v15, 32, v15
	v_lshl_add_u64 v[6:7], s[28:29], 0, v[192:193]
	v_mov_b32_e32 v207, v193
	v_readlane_b32 s24, v250, 34
	v_bitop3_b32 v16, v14, s12, v15 bitop3:0xde
	s_lshl_b32 s12, s19, 5
	v_lshl_add_u64 v[8:9], s[28:29], 0, v[206:207]
	v_mov_b32_e32 v211, v193
	v_readlane_b32 s25, v250, 35
	s_and_b32 s23, s12, 0x60
	s_add_i32 m0, s66, 0x18000
	v_lshl_add_u64 v[6:7], v[6:7], 0, s[16:17]
	v_lshl_add_u64 v[10:11], s[24:25], 0, v[210:211]
	v_mov_b32_e32 v209, v193
	s_lshl_b32 s12, s23, 7
	global_load_lds_dwordx4 v[6:7], off
	v_lshl_add_u64 v[6:7], v[8:9], 0, s[16:17]
	s_add_i32 m0, s66, 0x1a000
	s_add_i32 s75, s66, 0x8000
	v_lshl_add_u64 v[12:13], s[24:25], 0, v[208:209]
	v_bitop3_b32 v234, s12, v14, v15 bitop3:0xf6
	global_load_lds_dwordx4 v[6:7], off
	v_lshl_add_u64 v[6:7], v[10:11], 0, s[16:17]
	s_mov_b32 m0, s75
	s_add_i32 s76, s66, 0xa000
	v_readlane_b32 s12, v250, 40
	global_load_lds_dwordx4 v[6:7], off
	v_lshl_add_u64 v[6:7], v[12:13], 0, s[16:17]
	s_mov_b32 m0, s76
	v_readlane_b32 s13, v250, 41
	global_load_lds_dwordx4 v[6:7], off
	s_add_i32 m0, s66, 0x1c000
	v_lshl_add_u64 v[6:7], s[12:13], 0, v[192:193]
	global_load_lds_dwordx4 v[6:7], off
	v_lshl_add_u64 v[6:7], s[12:13], 0, v[206:207]
	s_add_i32 m0, s66, 0x1e000
	s_lshl_b32 s6, s20, 6
	global_load_lds_dwordx4 v[6:7], off
	s_waitcnt vmcnt(8)
	s_barrier
	v_lshlrev_b32_e32 v6, 15, v4
	v_and_b32_e32 v6, 0xffff0000, v6
	v_lshl_add_u32 v3, v3, 12, v6
	v_and_b32_e32 v4, 1, v4
	v_lshl_or_b32 v3, v4, 6, v3
	v_lshl_add_u32 v212, v5, 1, v3
	v_lshlrev_b32_e32 v3, 15, v0
	v_and_b32_e32 v3, 0xffff0000, v3
	s_waitcnt vmcnt(6)
	s_cmpk_lt_u32 s18, 0x100
	v_lshl_add_u32 v1, v1, 12, v3
	v_and_b32_e32 v0, 1, v0
	s_cselect_b64 s[0:1], -1, 0
	v_lshl_or_b32 v0, v0, 6, v1
	v_readlane_b32 s12, v249, 25
	v_writelane_b32 v248, s0, 58
	v_mov_b32_e32 v213, v193
	v_lshl_add_u32 v214, v2, 1, v0
	v_mov_b32_e32 v215, v193
	s_mov_b32 s80, 0
	v_add_u32_e32 v235, 0, v16
	v_readlane_b32 s20, v250, 58
	s_mov_b32 s40, s12
	s_mov_b64 s[18:19], s[24:25]
	s_barrier
	v_writelane_b32 v248, s1, 59
	v_readlane_b32 s13, v249, 26
	s_branch .LBB0_128

; #define PG8_STAGE(bufoff, gbase, voff) do { _Pragma("unroll") for (int _i = 0; _i < 2; ++_i) \
;         __builtin_amdgcn_global_load_lds((const unsigned*)((const char*)(gbase) + (voff)[_i]), (LAS unsigned*)(lds + (bufoff) + ldsw + _i * 8192), 16, 0, 0); } while (0)
; #define PG8_WAIT_V(n) asm volatile("s_waitcnt vmcnt(" #n ")" ::: "memory")
; #define PG8_BAR __builtin_amdgcn_s_barrier()
; template <class Epi, bool SP2 = true, bool ALIGN_EPI = true>
; __device__ __forceinline__ void gemm_phase(LAS unsigned char* lds, const Gemm g, const StaticOrder& S, const Epi& E, const int tid) {
;     ...
;     for (int i = 0; i < 2; ++i) { int R, C; stage_rc(tid * 16 + i * 8192, R, C); const int Rb = Epi::PERM ? ((R & ~31) + perm32(R & 31)) : R;
;         voffA[i] = (unsigned)(R * K + C) * 2u; voffB[i] = (unsigned)(Rb * K + C) * 2u; }
;     const size_t kstep = (size_t)(BK * 2);
;     const size_t hstep = (size_t)HALF * K * 2;
;     const size_t tstep = 2 * hstep;
;     const unsigned ldsw = (unsigned)wid * 1024u;
;     const int aoff = lds_byte(wr * 64 + fr, fq * 8), boff = lds_byte(wc * 32 + fr, fq * 8);
;     ...
;     const char* cA = (const char*)g.A + (size_t)cur.pm * tstep; const char* cB = (const char*)g.Bt + (size_t)cur.pn * tstep;
;     if constexpr (SP2) {
;         PG8_STAGE(PG8_SB(0, 0), cB, voffB); PG8_STAGE(PG8_SB(0, 1), cB + hstep, voffB); PG8_STAGE(PG8_SA(0, 0), cA, voffA); PG8_STAGE(PG8_SA(0, 1), cA + hstep, voffA);
;         if (wr == 1) PG8_BAR;
;         PG8_WAIT_V(2); PG8_BAR;
;         PG8_STAGE(PG8_SB(1, 0), cB + kstep, voffB); PG8_STAGE(PG8_SA(1, 0), cA + kstep, voffA); PG8_STAGE(PG8_SB(1, 1), cB + hstep + kstep, voffB);
;         PG8_WAIT_V(6); PG8_BAR;
.LBB0_161:
	s_lshl_b32 s24, s82, 11
	v_readlane_b32 s28, v249, 21
	s_ashr_i32 s25, s24, 31
	v_readlane_b32 s44, v248, 5
	v_mov_b32_e32 v133, v193
	v_readlane_b32 s29, v249, 22
	s_lshl_b64 s[24:25], s[24:25], 2
	v_readlane_b32 s48, v248, 9
	v_readlane_b32 s50, v248, 11
	v_lshl_add_u64 v[6:7], s[28:29], 0, v[132:133]
	v_mov_b32_e32 v129, v193
	v_readlane_b32 s40, v249, 17
	v_readlane_b32 s49, v248, 10
	v_readlane_b32 s51, v248, 12
	s_add_u32 s50, s48, s24
	v_lshl_add_u64 v[8:9], s[28:29], 0, v[128:129]
	v_mov_b32_e32 v135, v193
	v_readlane_b32 s41, v249, 18
	s_addc_u32 s51, s49, s25
	s_add_i32 m0, s39, 0x18000
	v_lshl_add_u64 v[6:7], v[6:7], 0, s[16:17]
	v_lshl_add_u64 v[10:11], s[40:41], 0, v[134:135]
	v_mov_b32_e32 v131, v193
	global_load_lds_dwordx4 v[6:7], off
	v_lshl_add_u64 v[6:7], v[8:9], 0, s[16:17]
	s_add_i32 m0, s39, 0x1a000
	s_add_i32 s76, s39, 0x8000
	v_lshl_add_u64 v[12:13], s[40:41], 0, v[130:131]
	global_load_lds_dwordx4 v[6:7], off
	v_lshl_add_u64 v[6:7], v[10:11], 0, s[16:17]
	s_mov_b32 m0, s76
	s_add_i32 s70, s39, 0xa000
	v_readlane_b32 s24, v249, 23
	global_load_lds_dwordx4 v[6:7], off
	v_lshl_add_u64 v[6:7], v[12:13], 0, s[16:17]
	s_mov_b32 m0, s70
	v_readlane_b32 s25, v249, 24
	global_load_lds_dwordx4 v[6:7], off
	s_add_i32 m0, s39, 0x1c000
	v_lshl_add_u64 v[6:7], s[24:25], 0, v[132:133]
	global_load_lds_dwordx4 v[6:7], off
	v_lshl_add_u64 v[6:7], s[24:25], 0, v[128:129]
	s_add_i32 m0, s39, 0x1e000
	v_bfe_u32 v151, v231, 4, 2
	global_load_lds_dwordx4 v[6:7], off
	s_waitcnt vmcnt(8)
	s_barrier
	v_lshlrev_b32_e32 v6, 14, v4
	v_and_b32_e32 v150, 15, v231
	v_lshlrev_b32_e32 v14, 4, v151
	v_lshlrev_b32_e32 v15, 2, v231
	v_and_b32_e32 v6, 0xffff8000, v6
	s_and_b32 s12, s18, 3
	v_lshl_or_b32 v14, v150, 6, v14
	s_lshl_b32 s13, s20, 13
	v_and_b32_e32 v15, 32, v15
	v_lshl_add_u32 v3, v3, 11, v6
	v_and_b32_e32 v4, 1, v4
	s_lshl_b32 s80, s20, 6
	v_bitop3_b32 v16, v14, s13, v15 bitop3:0xde
	s_lshl_b32 s74, s12, 5
	s_lshl_b32 s13, s12, 12
	v_lshl_or_b32 v3, v4, 6, v3
	s_cmpk_lt_u32 s19, 0x100
	v_lshl_add_u32 v136, v5, 1, v3
	v_lshlrev_b32_e32 v3, 14, v0
	s_cselect_b64 s[0:1], -1, 0
	s_lshl_b32 s23, s12, 6
	s_lshl_b32 s12, s18, 7
	v_and_b32_e32 v3, 0xffff8000, v3
	s_waitcnt vmcnt(6)
	s_bfe_u32 s72, s18, 0x10001
	s_and_b32 s12, s12, 0x80
	v_readlane_b32 s18, v251, 14
	v_lshl_add_u32 v1, v1, 11, v3
	v_and_b32_e32 v0, 1, v0
	v_bitop3_b32 v152, s13, v14, v15 bitop3:0xf6
	v_readlane_b32 s19, v251, 15
	s_add_u32 s8, s18, s12
	v_lshl_or_b32 v0, v0, 6, v1
	v_readlane_b32 s12, v249, 11
	v_readlane_b32 s45, v248, 6
	v_readlane_b32 s46, v248, 7
	v_readlane_b32 s47, v248, 8
	v_readlane_b32 s52, v248, 13
	v_readlane_b32 s53, v248, 14
	v_readlane_b32 s54, v248, 15
	v_readlane_b32 s55, v248, 16
	v_readlane_b32 s56, v248, 17
	v_readlane_b32 s57, v248, 18
	v_readlane_b32 s58, v248, 19
	v_readlane_b32 s59, v248, 20
	v_writelane_b32 v248, s0, 58
	s_addc_u32 s9, s19, 0
	v_mov_b32_e32 v137, v193
	v_lshl_add_u32 v138, v2, 1, v0
	v_mov_b32_e32 v139, v193
	s_mov_b32 s73, 0
	v_add_u32_e32 v153, 0, v16
	s_lshl_b32 s71, s74, 1
	v_readlane_b32 s20, v250, 43
	s_mov_b32 s44, s12
	s_mov_b64 s[18:19], s[28:29]
	s_mov_b64 s[24:25], s[40:41]
	s_barrier
	v_writelane_b32 v248, s1, 59
	v_readlane_b32 s13, v249, 12
	s_branch .LBB0_164

; #define PG8_STAGE(bufoff, gbase, voff) do { _Pragma("unroll") for (int _i = 0; _i < 2; ++_i) \
;         __builtin_amdgcn_global_load_lds((const unsigned*)((const char*)(gbase) + (voff)[_i]), (LAS unsigned*)(lds + (bufoff) + ldsw + _i * 8192), 16, 0, 0); } while (0)
; #define PG8_WAIT_V(n) asm volatile("s_waitcnt vmcnt(" #n ")" ::: "memory")
; #define PG8_BAR __builtin_amdgcn_s_barrier()
; template <class Epi, bool SP2 = true, bool ALIGN_EPI = true>
; __device__ __forceinline__ void gemm_phase(LAS unsigned char* lds, const Gemm g, const StaticOrder& S, const Epi& E, const int tid) {
;     ...
;     for (int i = 0; i < 2; ++i) { int R, C; stage_rc(tid * 16 + i * 8192, R, C); const int Rb = Epi::PERM ? ((R & ~31) + perm32(R & 31)) : R;
;         voffA[i] = (unsigned)(R * K + C) * 2u; voffB[i] = (unsigned)(Rb * K + C) * 2u; }
;     const size_t kstep = (size_t)(BK * 2);
;     const size_t hstep = (size_t)HALF * K * 2;
;     const size_t tstep = 2 * hstep;
;     const unsigned ldsw = (unsigned)wid * 1024u;
;     const int aoff = lds_byte(wr * 64 + fr, fq * 8), boff = lds_byte(wc * 32 + fr, fq * 8);
;     ...
;     const char* cA = (const char*)g.A + (size_t)cur.pm * tstep; const char* cB = (const char*)g.Bt + (size_t)cur.pn * tstep;
;     if constexpr (SP2) {
;         PG8_STAGE(PG8_SB(0, 0), cB, voffB); PG8_STAGE(PG8_SB(0, 1), cB + hstep, voffB); PG8_STAGE(PG8_SA(0, 0), cA, voffA); PG8_STAGE(PG8_SA(0, 1), cA + hstep, voffA);
;         if (wr == 1) PG8_BAR;
;         PG8_WAIT_V(2); PG8_BAR;
;         PG8_STAGE(PG8_SB(1, 0), cB + kstep, voffB); PG8_STAGE(PG8_SA(1, 0), cA + kstep, voffA); PG8_STAGE(PG8_SB(1, 1), cB + hstep + kstep, voffB);
;         PG8_WAIT_V(6); PG8_BAR;
.LBB0_315:
	s_mul_i32 s12, s82, 0xc00
	s_ashr_i32 s13, s12, 31
	v_readlane_b32 s44, v248, 28
	s_lshl_b64 s[12:13], s[12:13], 2
	v_readlane_b32 s46, v248, 30
	v_readlane_b32 s56, v248, 40
	v_readlane_b32 s47, v248, 31
	v_readlane_b32 s57, v248, 41
	s_add_u32 s46, s56, s12
	v_readlane_b32 s48, v248, 32
	v_readlane_b32 s58, v248, 42
	s_addc_u32 s47, s57, s13
	v_bfe_u32 v214, v231, 4, 2
	v_readlane_b32 s28, v249, 37
	v_readlane_b32 s49, v248, 33
	v_readlane_b32 s59, v248, 43
	s_add_u32 s48, s58, s12
	v_and_b32_e32 v215, 15, v231
	v_lshlrev_b32_e32 v16, 4, v214
	v_lshlrev_b32_e32 v17, 2, v231
	v_readlane_b32 s29, v249, 38
	s_addc_u32 s49, s59, s13
	v_lshl_or_b32 v16, v215, 6, v16
	s_lshl_b32 s12, s24, 13
	v_and_b32_e32 v17, 32, v17
	v_lshl_add_u64 v[8:9], s[28:29], 0, v[192:193]
	v_mov_b32_e32 v161, v193
	v_readlane_b32 s42, v249, 33
	v_bitop3_b32 v18, v16, s12, v17 bitop3:0xde
	s_lshl_b32 s12, s19, 5
	v_lshl_add_u64 v[10:11], s[28:29], 0, v[160:161]
	v_readlane_b32 s43, v249, 34
	s_and_b32 s71, s12, 0x60
	s_add_i32 m0, s36, 0x18000
	v_lshl_add_u64 v[8:9], v[8:9], 0, s[16:17]
	v_lshl_add_u64 v[12:13], s[42:43], 0, v[192:193]
	s_lshl_b32 s12, s71, 7
	global_load_lds_dwordx4 v[8:9], off
	v_lshl_add_u64 v[8:9], v[10:11], 0, s[16:17]
	s_add_i32 m0, s36, 0x1a000
	s_add_i32 s72, s36, 0x8000
	v_lshl_add_u64 v[14:15], s[42:43], 0, v[160:161]
	v_bitop3_b32 v216, s12, v16, v17 bitop3:0xf6
	global_load_lds_dwordx4 v[8:9], off
	v_lshl_add_u64 v[8:9], v[12:13], 0, s[16:17]
	s_mov_b32 m0, s72
	s_add_i32 s73, s36, 0xa000
	v_readlane_b32 s12, v249, 39
	global_load_lds_dwordx4 v[8:9], off
	v_lshl_add_u64 v[8:9], v[14:15], 0, s[16:17]
	s_mov_b32 m0, s73
	v_readlane_b32 s13, v249, 40
	global_load_lds_dwordx4 v[8:9], off
	s_add_i32 m0, s36, 0x1c000
	v_lshl_add_u64 v[8:9], s[12:13], 0, v[192:193]
	global_load_lds_dwordx4 v[8:9], off
	v_lshl_add_u64 v[8:9], s[12:13], 0, v[160:161]
	s_add_i32 m0, s36, 0x1e000
	v_lshlrev_b32_e32 v5, 13, v5
	global_load_lds_dwordx4 v[8:9], off
	s_waitcnt vmcnt(8)
	s_barrier
	v_lshlrev_b32_e32 v0, 13, v0
	v_and_b32_e32 v5, 0x7fffc000, v5
	v_and_b32_e32 v0, 0x7fffc000, v0
	v_lshl_add_u32 v4, v4, 10, v5
	v_lshl_add_u32 v0, v1, 10, v0
	s_lshl_b32 s70, s24, 6
	s_waitcnt vmcnt(6)
	v_or_b32_e32 v4, v4, v6
	v_or_b32_e32 v0, v0, v2
	v_readlane_b32 s52, v248, 36
	v_readlane_b32 s53, v248, 37
	s_cmpk_lt_u32 s18, 0x100
	v_add_lshl_u32 v4, v4, v7, 1
	v_mov_b32_e32 v5, v193
	s_mov_b64 s[0:1], 0x40080
	v_add_lshl_u32 v0, v0, v3, 1
	v_mov_b32_e32 v1, v193
	v_readlane_b32 s12, v249, 25
	v_readlane_b32 s54, v248, 38
	s_cselect_b64 s[52:53], -1, 0
	v_lshl_add_u64 v[162:163], v[4:5], 0, s[0:1]
	v_lshl_add_u64 v[164:165], v[0:1], 0, s[0:1]
	s_mov_b32 s74, 0
	v_add_u32_e32 v217, 0, v18
	v_readlane_b32 s75, v250, 58
	s_mov_b32 s76, s12
	s_mov_b64 s[18:19], s[28:29]
	s_mov_b64 s[24:25], s[42:43]
	v_readlane_b32 s45, v248, 29
	v_readlane_b32 s50, v248, 34
	v_readlane_b32 s51, v248, 35
	v_readlane_b32 s55, v248, 39
	s_barrier
	v_readlane_b32 s13, v249, 26
	s_branch .LBB0_318

; #define PG8_STAGE(bufoff, gbase, voff) do { _Pragma("unroll") for (int _i = 0; _i < 2; ++_i) \
;         __builtin_amdgcn_global_load_lds((const unsigned*)((const char*)(gbase) + (voff)[_i]), (LAS unsigned*)(lds + (bufoff) + ldsw + _i * 8192), 16, 0, 0); } while (0)
; #define PG8_WAIT_V(n) asm volatile("s_waitcnt vmcnt(" #n ")" ::: "memory")
; #define PG8_BAR __builtin_amdgcn_s_barrier()
; template <class Epi, bool SP2 = true, bool ALIGN_EPI = true>
; __device__ __forceinline__ void gemm_phase(LAS unsigned char* lds, const Gemm g, const StaticOrder& S, const Epi& E, const int tid) {
;     ...
;     for (int i = 0; i < 2; ++i) { int R, C; stage_rc(tid * 16 + i * 8192, R, C); const int Rb = Epi::PERM ? ((R & ~31) + perm32(R & 31)) : R;
;         voffA[i] = (unsigned)(R * K + C) * 2u; voffB[i] = (unsigned)(Rb * K + C) * 2u; }
;     const size_t kstep = (size_t)(BK * 2);
;     const size_t hstep = (size_t)HALF * K * 2;
;     const size_t tstep = 2 * hstep;
;     const unsigned ldsw = (unsigned)wid * 1024u;
;     const int aoff = lds_byte(wr * 64 + fr, fq * 8), boff = lds_byte(wc * 32 + fr, fq * 8);
;     ...
;     const char* cA = (const char*)g.A + (size_t)cur.pm * tstep; const char* cB = (const char*)g.Bt + (size_t)cur.pn * tstep;
;     if constexpr (SP2) {
;         PG8_STAGE(PG8_SB(0, 0), cB, voffB); PG8_STAGE(PG8_SB(0, 1), cB + hstep, voffB); PG8_STAGE(PG8_SA(0, 0), cA, voffA); PG8_STAGE(PG8_SA(0, 1), cA + hstep, voffA);
;         if (wr == 1) PG8_BAR;
;         PG8_WAIT_V(2); PG8_BAR;
;         PG8_STAGE(PG8_SB(1, 0), cB + kstep, voffB); PG8_STAGE(PG8_SA(1, 0), cA + kstep, voffA); PG8_STAGE(PG8_SB(1, 1), cB + hstep + kstep, voffB);
;         PG8_WAIT_V(6); PG8_BAR;
.LBB0_435:
	s_add_i32 s12, s3, 9
	s_cmp_lt_u32 s12, 21
	s_cselect_b64 s[18:19], -1, 0
	s_cmp_eq_u32 s67, 1
	s_cselect_b64 s[42:43], -1, 0
	s_and_b64 s[44:45], s[42:43], exec
	s_mul_i32 s12, s82, 3
	s_cselect_b32 s13, -1, 1
	s_and_b64 s[18:19], s[18:19], s[42:43]
	s_add_i32 s12, s12, s13
	s_and_b64 s[42:43], s[18:19], exec
	v_readlane_b32 s40, v248, 5
	v_readlane_b32 s41, v248, 6
	s_cselect_b32 s41, s41, s85
	s_cselect_b32 s40, s40, s84
	s_lshl_b32 s12, s12, 10
	v_readlane_b32 s42, v248, 7
	v_readlane_b32 s43, v248, 8
	v_readlane_b32 s44, v248, 9
	v_readlane_b32 s45, v248, 10
	v_readlane_b32 s46, v248, 11
	v_readlane_b32 s47, v248, 12
	s_ashr_i32 s13, s12, 31
	s_and_b64 s[42:43], s[18:19], exec
	s_mov_b64 s[44:45], s[84:85]
	s_cselect_b32 s43, 0, s13
	s_cselect_b32 s42, 0, s12
	s_mov_b64 s[46:47], s[86:87]
	v_readlane_b32 s72, v248, 28
	v_readlane_b32 s48, v248, 13
	s_lshl_b64 s[42:43], s[42:43], 2
	v_readlane_b32 s84, v248, 40
	v_readlane_b32 s49, v248, 14
	v_readlane_b32 s85, v248, 41
	s_add_u32 s48, s84, s42
	v_readlane_b32 s52, v248, 17
	v_readlane_b32 s86, v248, 42
	s_addc_u32 s49, s85, s43
	v_bfe_u32 v210, v231, 4, 2
	v_readlane_b32 s56, v249, 3
	v_readlane_b32 s53, v248, 18
	v_readlane_b32 s87, v248, 43
	s_add_u32 s52, s86, s42
	v_and_b32_e32 v211, 15, v231
	v_lshlrev_b32_e32 v16, 4, v210
	v_lshlrev_b32_e32 v17, 2, v231
	v_readlane_b32 s57, v249, 4
	s_addc_u32 s53, s87, s43
	v_lshl_or_b32 v16, v211, 6, v16
	s_lshl_b32 s12, s28, 13
	v_and_b32_e32 v17, 32, v17
	v_lshl_add_u64 v[8:9], s[56:57], 0, v[192:193]
	v_mov_b32_e32 v161, v193
	v_readlane_b32 s92, v250, 63
	v_bitop3_b32 v18, v16, s12, v17 bitop3:0xde
	s_lshl_b32 s12, s25, 5
	v_lshl_add_u64 v[10:11], s[56:57], 0, v[160:161]
	v_readlane_b32 s93, v249, 0
	s_and_b32 s71, s12, 0x60
	s_add_i32 m0, s36, 0x18000
	v_lshl_add_u64 v[8:9], v[8:9], 0, s[16:17]
	v_lshl_add_u64 v[12:13], s[92:93], 0, v[192:193]
	v_readlane_b32 s73, v248, 29
	s_lshl_b32 s12, s71, 7
	global_load_lds_dwordx4 v[8:9], off
	v_lshl_add_u64 v[8:9], v[10:11], 0, s[16:17]
	s_add_i32 m0, s36, 0x1a000
	s_add_i32 s72, s36, 0x8000
	v_lshl_add_u64 v[14:15], s[92:93], 0, v[160:161]
	v_bitop3_b32 v212, s12, v16, v17 bitop3:0xf6
	global_load_lds_dwordx4 v[8:9], off
	v_lshl_add_u64 v[8:9], v[12:13], 0, s[16:17]
	s_mov_b32 m0, s72
	s_add_i32 s73, s36, 0xa000
	v_readlane_b32 s12, v249, 5
	global_load_lds_dwordx4 v[8:9], off
	v_lshl_add_u64 v[8:9], v[14:15], 0, s[16:17]
	s_mov_b32 m0, s73
	v_readlane_b32 s13, v249, 6
	global_load_lds_dwordx4 v[8:9], off
	s_add_i32 m0, s36, 0x1c000
	v_lshl_add_u64 v[8:9], s[12:13], 0, v[192:193]
	global_load_lds_dwordx4 v[8:9], off
	v_lshl_add_u64 v[8:9], s[12:13], 0, v[160:161]
	s_add_i32 m0, s36, 0x1e000
	s_lshl_b32 s70, s28, 6
	global_load_lds_dwordx4 v[8:9], off
	s_waitcnt vmcnt(8)
	s_barrier
	v_readlane_b32 s12, v249, 7
	v_readlane_b32 s54, v248, 19
	v_readlane_b32 s55, v248, 20
	s_cmpk_lt_u32 s24, 0x100
	v_readlane_b32 s13, v249, 8
	s_movk_i32 s6, 0xb00
	s_cselect_b64 s[54:55], -1, 0
	s_nor_b64 s[58:59], s[18:19], s[12:13]
	v_lshrrev_b32_e32 v5, 1, v5
	v_mul_lo_u32 v4, v4, s6
	s_mov_b32 s12, 0xb000
	v_mad_u64_u32 v[4:5], s[18:19], v5, s12, v[4:5]
	v_or_b32_e32 v4, v4, v6
	v_add_lshl_u32 v4, v4, v7, 1
	v_mov_b32_e32 v5, v193
	s_mov_b64 s[24:25], 0xb0080
	v_lshl_add_u64 v[162:163], v[4:5], 0, s[24:25]
	v_lshrrev_b32_e32 v4, 1, v0
	v_mul_lo_u32 v0, v1, s6
	v_mad_u64_u32 v[0:1], s[18:19], v4, s12, v[0:1]
	s_waitcnt vmcnt(6)
	v_or_b32_e32 v0, v0, v2
	v_readlane_b32 s76, v248, 32
	v_readlane_b32 s78, v248, 34
	s_mov_b64 s[86:87], s[46:47]
	v_add_lshl_u32 v0, v0, v3, 1
	v_mov_b32_e32 v1, v193
	v_readlane_b32 s12, v249, 25
	s_mov_b32 s22, 0
	v_readlane_b32 s74, v248, 30
	v_readlane_b32 s75, v248, 31
	s_mov_b64 s[84:85], s[44:45]
	v_lshl_add_u64 v[164:165], v[0:1], 0, s[24:25]
	v_add_u32_e32 v213, 0, v18
	v_readlane_b32 s76, v250, 58
	s_mov_b32 s78, s12
	s_mov_b64 s[18:19], s[56:57]
	s_mov_b64 s[24:25], s[92:93]
	v_readlane_b32 s50, v248, 15
	v_readlane_b32 s51, v248, 16
	v_readlane_b32 s77, v248, 33
	v_readlane_b32 s79, v248, 35
	v_readlane_b32 s80, v248, 36
	v_readlane_b32 s81, v248, 37
	v_readlane_b32 s82, v248, 38
	v_readlane_b32 s83, v248, 39
	s_barrier
	v_readlane_b32 s13, v249, 26
	s_branch .LBB0_438

; #define PG8_STAGE(bufoff, gbase, voff) do { _Pragma("unroll") for (int _i = 0; _i < 2; ++_i) \
;         __builtin_amdgcn_global_load_lds((const unsigned*)((const char*)(gbase) + (voff)[_i]), (LAS unsigned*)(lds + (bufoff) + ldsw + _i * 8192), 16, 0, 0); } while (0)
; #define PG8_WAIT_V(n) asm volatile("s_waitcnt vmcnt(" #n ")" ::: "memory")
; #define PG8_BAR __builtin_amdgcn_s_barrier()
; template <class Epi, bool SP2 = true, bool ALIGN_EPI = true>
; __device__ __forceinline__ void gemm_phase(LAS unsigned char* lds, const Gemm g, const StaticOrder& S, const Epi& E, const int tid) {
;     ...
;     for (int i = 0; i < 2; ++i) { int R, C; stage_rc(tid * 16 + i * 8192, R, C); const int Rb = Epi::PERM ? ((R & ~31) + perm32(R & 31)) : R;
;         voffA[i] = (unsigned)(R * K + C) * 2u; voffB[i] = (unsigned)(Rb * K + C) * 2u; }
;     const size_t kstep = (size_t)(BK * 2);
;     const size_t hstep = (size_t)HALF * K * 2;
;     const size_t tstep = 2 * hstep;
;     const unsigned ldsw = (unsigned)wid * 1024u;
;     const int aoff = lds_byte(wr * 64 + fr, fq * 8), boff = lds_byte(wc * 32 + fr, fq * 8);
;     ...
;     const char* cA = (const char*)g.A + (size_t)cur.pm * tstep; const char* cB = (const char*)g.Bt + (size_t)cur.pn * tstep;
;     if constexpr (SP2) {
;         PG8_STAGE(PG8_SB(0, 0), cB, voffB); PG8_STAGE(PG8_SB(0, 1), cB + hstep, voffB); PG8_STAGE(PG8_SA(0, 0), cA, voffA); PG8_STAGE(PG8_SA(0, 1), cA + hstep, voffA);
;         if (wr == 1) PG8_BAR;
;         PG8_WAIT_V(2); PG8_BAR;
;         PG8_STAGE(PG8_SB(1, 0), cB + kstep, voffB); PG8_STAGE(PG8_SA(1, 0), cA + kstep, voffA); PG8_STAGE(PG8_SB(1, 1), cB + hstep + kstep, voffB);
;         PG8_WAIT_V(6); PG8_BAR;
.LBB0_508:
	v_readlane_b32 s28, v250, 54
	v_readlane_b32 s29, v250, 55
	v_mov_b32_e32 v129, v193
	v_readlane_b32 s42, v250, 50
	v_lshl_add_u64 v[6:7], s[28:29], 0, v[192:193]
	v_lshl_add_u64 v[8:9], s[28:29], 0, v[128:129]
	v_mov_b32_e32 v133, v193
	v_readlane_b32 s43, v250, 51
	s_add_i32 m0, s22, 0x18000
	v_lshl_add_u64 v[6:7], v[6:7], 0, s[16:17]
	v_lshl_add_u64 v[10:11], s[42:43], 0, v[132:133]
	v_mov_b32_e32 v131, v193
	global_load_lds_dwordx4 v[6:7], off
	v_lshl_add_u64 v[6:7], v[8:9], 0, s[16:17]
	s_add_i32 m0, s22, 0x1a000
	s_add_i32 s57, s22, 0x8000
	v_lshl_add_u64 v[12:13], s[42:43], 0, v[130:131]
	global_load_lds_dwordx4 v[6:7], off
	v_lshl_add_u64 v[6:7], v[10:11], 0, s[16:17]
	s_mov_b32 m0, s57
	s_add_i32 s58, s22, 0xa000
	v_readlane_b32 s12, v250, 56
	global_load_lds_dwordx4 v[6:7], off
	v_lshl_add_u64 v[6:7], v[12:13], 0, s[16:17]
	s_mov_b32 m0, s58
	v_readlane_b32 s13, v250, 57
	global_load_lds_dwordx4 v[6:7], off
	s_add_i32 m0, s22, 0x1c000
	v_lshl_add_u64 v[6:7], s[12:13], 0, v[192:193]
	global_load_lds_dwordx4 v[6:7], off
	v_lshl_add_u64 v[6:7], s[12:13], 0, v[128:129]
	s_add_i32 m0, s22, 0x1e000
	v_bfe_u32 v139, v231, 4, 2
	global_load_lds_dwordx4 v[6:7], off
	s_waitcnt vmcnt(8)
	s_barrier
	v_and_b32_e32 v138, 15, v231
	v_lshlrev_b32_e32 v6, 4, v139
	v_lshlrev_b32_e32 v7, 2, v231
	v_lshl_or_b32 v6, v138, 6, v6
	s_lshl_b32 s12, s24, 13
	v_and_b32_e32 v7, 32, v7
	v_bitop3_b32 v8, v6, s12, v7 bitop3:0xde
	s_lshl_b32 s12, s19, 5
	s_and_b32 s66, s12, 0x60
	s_lshl_b32 s12, s66, 7
	v_bitop3_b32 v140, s12, v6, v7 bitop3:0xf6
	v_lshlrev_b32_e32 v6, 14, v4
	v_and_b32_e32 v6, 0xffff8000, v6
	v_lshl_add_u32 v3, v3, 11, v6
	v_and_b32_e32 v4, 1, v4
	v_lshl_or_b32 v3, v4, 6, v3
	v_lshl_add_u32 v134, v5, 1, v3
	v_lshlrev_b32_e32 v3, 14, v0
	v_and_b32_e32 v3, 0xffff8000, v3
	s_lshl_b32 s59, s24, 6
	s_waitcnt vmcnt(6)
	v_lshl_add_u32 v1, v1, 11, v3
	v_and_b32_e32 v0, 1, v0
	s_cmpk_lt_u32 s18, 0x100
	v_lshl_or_b32 v0, v0, 6, v1
	v_readlane_b32 s12, v250, 44
	s_cselect_b64 s[44:45], -1, 0
	v_mov_b32_e32 v135, v193
	v_lshl_add_u32 v136, v2, 1, v0
	v_mov_b32_e32 v137, v193
	s_mov_b32 s69, 0
	v_add_u32_e32 v141, 0, v8
	v_readlane_b32 s70, v250, 42
	s_mov_b32 s71, s12
	s_mov_b64 s[18:19], s[28:29]
	s_mov_b64 s[24:25], s[42:43]
	s_barrier
	v_readlane_b32 s13, v250, 45
	s_branch .LBB0_511
